# S5 scan chunk restructured: MFMAs back-to-back into distinct registers, all step-pair reads up front with counted lgkmcnt, complex state update as 4 v_fma_f32 (f32), readout reads batched
# speedup vs baseline: 1.0046x; 1.0046x over previous
; DI void phase_scan(const Params& p, int j, unsigned char* shm, int wv) {
;     ...
; #pragma unroll
;       for (int nb = 0; nb < 8; ++nb) {
;         f32x4 z = {0.f, 0.f, 0.f, 0.f};
;         f32x4 r4 = __builtin_amdgcn_mfma_f32_16x16x16bf16_1k(ucur, bop[nb], z, 0, 0, 0);
; #pragma unroll
;         for (int jj = 0; jj < 4; ++jj) bu[(quad * 4 + jj) * 132 + nb * 16 + col] = r4[jj];
;       }
;       __builtin_amdgcn_wave_barrier();
;       float2 bv[16];
; #pragma unroll
;       for (int t = 0; t < 16; ++t) bv[t] = *(const float2*)(bu + t * 132 + 2 * pst);
; #pragma unroll
;       for (int t = 0; t < 16; ++t) {
;         const float nr = abr * hr - abi * hi + bv[t].x;
;         const float ni = abr * hi + abi * hr + bv[t].y;
;         hr = nr; hi = ni;
;         *(unsigned*)(Hl + t * 136 + 2 * pst) = pack2(hr, hi);
;       }
;       __builtin_amdgcn_wave_barrier();
;       f32x4 y = {0.f, 0.f, 0.f, 0.f};
; #pragma unroll
;       for (int kb = 0; kb < 4; ++kb) {
;         bf16x8 af = *(const bf16x8*)(Hl + col * 136 + kb * 32 + quad * 8);
;         y = __builtin_amdgcn_mfma_f32_16x16x32_bf16(cop[kb], af, y, 0, 0, 0);
;       }
.LBB0_866:
	s_waitcnt lgkmcnt(3)
	v_mfma_f32_16x16x16_bf16 v[74:77], v[34:35], v[2:3], 0
	v_add_u32_e32 v52, 0x400, v91
	v_add_u32_e32 v57, 0x1800, v92
	s_cmp_gt_u32 s1, 15
	v_mfma_f32_16x16x16_bf16 v[78:81], v[34:35], v[4:5], 0
	s_cselect_b64 s[8:9], -1, 0
	v_mfma_f32_16x16x16_bf16 v[102:105], v[34:35], v[6:7], 0
	v_mfma_f32_16x16x16_bf16 v[106:109], v[34:35], v[8:9], 0
	v_mfma_f32_16x16x16_bf16 v[110:113], v[34:35], v[10:11], 0
	v_mfma_f32_16x16x16_bf16 v[114:117], v[34:35], v[12:13], 0
	v_mfma_f32_16x16x16_bf16 v[118:121], v[34:35], v[14:15], 0
	v_mfma_f32_16x16x16_bf16 v[34:37], v[34:35], v[16:17], 0
	s_nop 1
	ds_write2_b32 v91, v74, v78 offset1:16
	ds_write2_b32 v91, v75, v79 offset0:132 offset1:148
	ds_write2_b32 v52, v76, v80 offset0:8 offset1:24
	ds_write2_b32 v52, v77, v81 offset0:140 offset1:156
	ds_write2_b32 v91, v102, v106 offset0:32 offset1:48
	ds_write2_b32 v91, v103, v107 offset0:164 offset1:180
	ds_write2_b32 v52, v104, v108 offset0:40 offset1:56
	ds_write2_b32 v52, v105, v109 offset0:172 offset1:188
	ds_write2_b32 v91, v110, v114 offset0:64 offset1:80
	ds_write2_b32 v91, v111, v115 offset0:196 offset1:212
	ds_write2_b32 v52, v112, v116 offset0:72 offset1:88
	ds_write2_b32 v52, v113, v117 offset0:204 offset1:220
	s_waitcnt lgkmcnt(11)
	ds_write2_b32 v91, v118, v34 offset0:96 offset1:112
	ds_write2_b32 v91, v119, v35 offset0:228 offset1:244
	ds_write2_b32 v52, v120, v36 offset0:104 offset1:120
	ds_write2_b32 v52, v121, v37 offset0:236 offset1:252
	ds_read2_b64 v[34:37], v92 offset1:66
	ds_read2_b64 v[102:105], v92 offset0:132 offset1:198
	v_add_u32_e32 v128, 0x800, v92
	v_add_u32_e32 v129, 0x1000, v92
	ds_read2_b64 v[106:109], v128 offset0:8 offset1:74
	ds_read2_b64 v[110:113], v128 offset0:140 offset1:206
	ds_read2_b64 v[114:117], v129 offset0:16 offset1:82
	ds_read2_b64 v[118:121], v129 offset0:148 offset1:214
	ds_read2_b64 v[74:77], v57 offset0:24 offset1:90
	ds_read2_b64 v[78:81], v57 offset0:156 offset1:222
	s_waitcnt lgkmcnt(7)
	v_fma_f32 v34, v42, v48, v34
	v_fma_f32 v35, v43, v49, v35
	v_fma_f32 v34, -v39, v49, v34
	v_fma_f32 v35, v38, v48, v35
	v_fma_f32 v36, v42, v34, v36
	v_fma_f32 v37, v43, v35, v37
	v_fma_f32 v36, -v39, v35, v36
	v_fma_f32 v37, v38, v34, v37
	v_cvt_pk_bf16_f32 v122, v34, v35
	v_add_u32_e32 v124, 0x2000, v93
	v_cvt_pk_bf16_f32 v123, v36, v37
	ds_write2_b32 v124, v122, v123 offset0:64 offset1:132
	s_waitcnt lgkmcnt(7)
	v_fma_f32 v102, v42, v36, v102
	v_fma_f32 v103, v43, v37, v103
	v_fma_f32 v102, -v39, v37, v102
	v_fma_f32 v103, v38, v36, v103
	v_fma_f32 v104, v42, v102, v104
	v_fma_f32 v105, v43, v103, v105
	v_fma_f32 v104, -v39, v103, v104
	v_fma_f32 v105, v38, v102, v105
	v_cvt_pk_bf16_f32 v125, v102, v103
	v_add_u32_e32 v127, 0x2200, v93
	v_cvt_pk_bf16_f32 v126, v104, v105
	ds_write2_b32 v127, v125, v126 offset0:72 offset1:140
	s_waitcnt lgkmcnt(7)
	v_fma_f32 v106, v42, v104, v106
	v_fma_f32 v107, v43, v105, v107
	v_fma_f32 v106, -v39, v105, v106
	v_fma_f32 v107, v38, v104, v107
	v_fma_f32 v108, v42, v106, v108
	v_fma_f32 v109, v43, v107, v109
	v_fma_f32 v108, -v39, v107, v108
	v_fma_f32 v109, v38, v106, v109
	v_cvt_pk_bf16_f32 v122, v106, v107
	v_add_u32_e32 v124, 0x2400, v93
	v_cvt_pk_bf16_f32 v123, v108, v109
	ds_write2_b32 v124, v122, v123 offset0:80 offset1:148
	s_waitcnt lgkmcnt(7)
	v_fma_f32 v110, v42, v108, v110
	v_fma_f32 v111, v43, v109, v111
	v_fma_f32 v110, -v39, v109, v110
	v_fma_f32 v111, v38, v108, v111
	v_fma_f32 v112, v42, v110, v112
	v_fma_f32 v113, v43, v111, v113
	v_fma_f32 v112, -v39, v111, v112
	v_fma_f32 v113, v38, v110, v113
	v_cvt_pk_bf16_f32 v125, v110, v111
	v_add_u32_e32 v127, 0x2600, v93
	v_cvt_pk_bf16_f32 v126, v112, v113
	ds_write2_b32 v127, v125, v126 offset0:88 offset1:156
	s_waitcnt lgkmcnt(7)
	v_fma_f32 v114, v42, v112, v114
	v_fma_f32 v115, v43, v113, v115
	v_fma_f32 v114, -v39, v113, v114
	v_fma_f32 v115, v38, v112, v115
	v_fma_f32 v116, v42, v114, v116
	v_fma_f32 v117, v43, v115, v117
	v_fma_f32 v116, -v39, v115, v116
	v_fma_f32 v117, v38, v114, v117
	v_cvt_pk_bf16_f32 v122, v114, v115
	v_add_u32_e32 v124, 0x2800, v93
	v_cvt_pk_bf16_f32 v123, v116, v117
	ds_write2_b32 v124, v122, v123 offset0:96 offset1:164
	s_waitcnt lgkmcnt(7)
	v_fma_f32 v118, v42, v116, v118
	v_fma_f32 v119, v43, v117, v119
	v_fma_f32 v118, -v39, v117, v118
	v_fma_f32 v119, v38, v116, v119
	v_fma_f32 v120, v42, v118, v120
	v_fma_f32 v121, v43, v119, v121
	v_fma_f32 v120, -v39, v119, v120
	v_fma_f32 v121, v38, v118, v121
	v_cvt_pk_bf16_f32 v125, v118, v119
	v_add_u32_e32 v127, 0x2a00, v93
	v_cvt_pk_bf16_f32 v126, v120, v121
	ds_write2_b32 v127, v125, v126 offset0:104 offset1:172
	s_waitcnt lgkmcnt(7)
	v_fma_f32 v74, v42, v120, v74
	v_fma_f32 v75, v43, v121, v75
	v_fma_f32 v74, -v39, v121, v74
	v_fma_f32 v75, v38, v120, v75
	v_fma_f32 v76, v42, v74, v76
	v_fma_f32 v77, v43, v75, v77
	v_fma_f32 v76, -v39, v75, v76
	v_fma_f32 v77, v38, v74, v77
	v_cvt_pk_bf16_f32 v122, v74, v75
	v_add_u32_e32 v124, 0x2c00, v93
	v_cvt_pk_bf16_f32 v123, v76, v77
	ds_write2_b32 v124, v122, v123 offset0:112 offset1:180
	s_waitcnt lgkmcnt(7)
	v_fma_f32 v78, v42, v76, v78
	v_fma_f32 v79, v43, v77, v79
	v_fma_f32 v78, -v39, v77, v78
	v_fma_f32 v79, v38, v76, v79
	v_fma_f32 v48, v42, v78, v80
	v_fma_f32 v49, v43, v79, v81
	v_fma_f32 v48, -v39, v79, v48
	v_fma_f32 v49, v38, v78, v49
	v_cvt_pk_bf16_f32 v125, v78, v79
	v_add_u32_e32 v127, 0x2e00, v93
	v_cvt_pk_bf16_f32 v126, v48, v49
	ds_write2_b32 v127, v125, v126 offset0:120 offset1:188
	v_or_b32_e32 v53, s20, v82
	ds_read_b128 v[34:37], v94 offset:8448
	ds_read_b128 v[74:77], v94 offset:8512
	ds_read_b128 v[102:105], v94 offset:8576
	ds_read_b128 v[106:109], v94 offset:8640
	s_waitcnt lgkmcnt(3)
	v_mfma_f32_16x16x32_bf16 v[34:37], v[18:21], v[34:37], 0
	s_waitcnt lgkmcnt(2)
	v_mfma_f32_16x16x32_bf16 v[34:37], v[22:25], v[74:77], v[34:37]
	s_waitcnt lgkmcnt(1)
	v_mfma_f32_16x16x32_bf16 v[34:37], v[26:29], v[102:105], v[34:37]
	s_waitcnt lgkmcnt(0)
	v_mfma_f32_16x16x32_bf16 v[34:37], v[30:33], v[106:109], v[34:37]
	s_and_saveexec_b64 s[12:13], s[24:25]
	s_xor_b64 s[12:13], exec, s[12:13]
	s_cbranch_execz .LBB0_872
	s_mov_b64 s[14:15], -1
	s_and_b64 vcc, exec, s[8:9]
	s_cbranch_vccz .LBB0_869
	v_sub_u32_e32 v52, v0, v53
	s_mov_b64 s[14:15], 0
